# scan compute waves prefetch the next chunk's first w/kk/ka operands from the DMA ring in the DPP gaps of the last two steps; loader confirms one more batch before each chunk barrier
# baseline (speedup 1.0000x reference)
.LBB0_1047:
	s_and_b64 vcc, exec, s[24:25]
	s_cbranch_vccz .LBB0_1279
	s_waitcnt vmcnt(0)
	v_mov_b32_e32 v4, v232
	s_nop 0
	v_ashrrev_i32_e32 v0, 6, v4
	v_and_b32_e32 v54, 15, v4
	v_cmp_gt_i32_e32 vcc, 4, v0
	v_lshlrev_b32_e32 v38, 2, v54
	s_barrier
	s_and_saveexec_b64 s[24:25], vcc
	s_xor_b64 s[24:25], exec, s[24:25]
	s_cbranch_execz .LBB0_1051
	v_lshlrev_b32_e32 v2, 2, v4
	s_waitcnt lgkmcnt(0)
	s_barrier
	v_and_b32_e32 v2, 0xc0, v2
	v_lshl_or_b32 v85, v0, 8, v2
	v_mov_b32_e32 v74, 0
	v_lshlrev_b32_e32 v83, 4, v54
	v_add3_u32 v87, 0, v85, v38
	s_mov_b32 s26, 0
	s_mov_b32 s96, 0x12800
	v_mov_b32_e32 v75, v74
	v_mov_b32_e32 v76, v74
	v_mov_b32_e32 v77, v74
	v_add_u32_e32 v88, 0x12800, v83
	ds_read_b128 v[108:111], v88 offset:4096
	ds_read_b128 v[100:103], v88
	ds_read_b128 v[120:123], v88 offset:8192
	ds_read_b128 v[112:115], v88 offset:4352
	ds_read_b128 v[104:107], v88 offset:256
	ds_read_b128 v[128:131], v88 offset:8448
	ds_read_b128 v[124:127], v88 offset:4608
	ds_read_b128 v[116:119], v88 offset:512
	s_waitcnt lgkmcnt(0)
	s_setprio 3
.LBB0_1050:
	s_and_b32 s2, s26, 1
	s_mul_i32 s3, s2, 0x5400
	v_lshlrev_b32_e32 v91, 2, v87
	v_lshl_add_u32 v91, s2, 14, v91
	s_add_i32 s2, s3, 0
	v_add_u32_e32 v0, s2, v85
	v_add_u32_e32 v89, s2, v83
	v_add_u32_e32 v90, s96, v83
	s_add_i32 s96, s96, 0x3000
	s_cmp_eq_u32 s96, 0x1e800
	s_cselect_b32 s96, 0x20200, s96
	s_cmp_eq_u32 s96, 0x23200
	s_cselect_b32 s96, 0x12800, s96
	v_add_u32_e32 v88, s96, v83
	ds_read_b128 v[14:17], v0 offset:20480
	ds_read_b128 v[10:13], v0 offset:20496
	ds_read_b128 v[6:9], v0 offset:20512
	ds_read_b128 v[2:5], v0 offset:20528
	ds_read_b128 v[54:57], v89 offset:16384
	ds_read_b128 v[26:29], v89 offset:16640
	ds_read_b128 v[78:81], v89 offset:4096
	ds_read_b128 v[58:61], v89 offset:4352
	ds_read_b128 v[30:33], v89 offset:4608
	ds_read_b128 v[22:25], v90 offset:8704
	ds_read_b128 v[18:21], v89 offset:16896
	v_pk_mul_f32 v[66:67], v[74:75], v[108:109]
	s_waitcnt lgkmcnt(4)
	v_pk_mul_f32 v[78:79], v[14:15], v[78:79] op_sel_hi:[0,1]
	v_pk_fma_f32 v[66:67], v[76:77], v[110:111], v[66:67]
	v_pk_mul_f32 v[80:81], v[14:15], v[80:81] op_sel_hi:[0,1]
	v_add_f32_e32 v66, v66, v67
	v_pk_fma_f32 v[62:63], v[74:75], v[100:101], v[78:79]
	v_pk_fma_f32 v[64:65], v[76:77], v[102:103], v[80:81]
	v_add_f32_dpp v66, v66, v66 quad_perm:[1,0,3,2] row_mask:0xf bank_mask:0xf bound_ctrl:1
	v_mov_b32_e32 v0, v17
	v_mov_b32_e32 v82, v13
	v_add_f32_dpp v66, v66, v66 quad_perm:[2,3,0,1] row_mask:0xf bank_mask:0xf bound_ctrl:1
	v_mov_b32_e32 v84, v9
	v_mov_b32_e32 v86, v5
	v_add_f32_dpp v66, v66, v66 row_half_mirror row_mask:0xf bank_mask:0xf bound_ctrl:1
	s_add_i32 s26, s26, 1
	s_cmpk_eq_i32 s26, 0x110
	v_add_f32_dpp v66, v66, v66 row_ror:8 row_mask:0xf bank_mask:0xf bound_ctrl:1
	v_pk_fma_f32 v[62:63], v[120:121], v[66:67], v[62:63] op_sel_hi:[1,0,1] neg_lo:[1,0,0] neg_hi:[1,0,0]
	v_pk_fma_f32 v[64:65], v[122:123], v[66:67], v[64:65] op_sel_hi:[1,0,1] neg_lo:[1,0,0] neg_hi:[1,0,0]
	v_pk_mul_f32 v[50:51], v[112:113], v[62:63]
	v_pk_mul_f32 v[46:47], v[104:105], v[62:63]
	v_pk_fma_f32 v[50:51], v[114:115], v[64:65], v[50:51]
	s_waitcnt lgkmcnt(3)
	v_pk_fma_f32 v[66:67], v[14:15], v[58:59], v[46:47] op_sel:[1,0,0]
	v_add_f32_e32 v47, v50, v51
	v_pk_mul_f32 v[48:49], v[106:107], v[64:65]
	v_pk_mul_f32 v[56:57], v[56:57], v[64:65]
	v_add_f32_dpp v68, v47, v47 quad_perm:[1,0,3,2] row_mask:0xf bank_mask:0xf bound_ctrl:1
	v_pk_fma_f32 v[14:15], v[14:15], v[60:61], v[48:49] op_sel:[1,0,0]
	v_pk_fma_f32 v[54:55], v[54:55], v[62:63], v[56:57]
	v_add_f32_dpp v68, v68, v68 quad_perm:[2,3,0,1] row_mask:0xf bank_mask:0xf bound_ctrl:1
	v_add_f32_e32 v92, v54, v55
	v_add_f32_dpp v68, v68, v68 row_half_mirror row_mask:0xf bank_mask:0xf bound_ctrl:1
	ds_read_b128 v[46:49], v90 offset:768
	ds_read_b128 v[50:53], v89 offset:4864
	ds_read_b128 v[54:57], v90 offset:4864
	ds_read_b128 v[58:61], v90 offset:8960
	ds_read_b128 v[62:65], v89 offset:17152
	v_add_f32_dpp v68, v68, v68 row_ror:8 row_mask:0xf bank_mask:0xf bound_ctrl:1
	v_pk_fma_f32 v[42:43], v[128:129], v[68:69], v[66:67] op_sel_hi:[1,0,1] neg_lo:[1,0,0] neg_hi:[1,0,0]
	v_pk_fma_f32 v[14:15], v[130:131], v[68:69], v[14:15] op_sel_hi:[1,0,1] neg_lo:[1,0,0] neg_hi:[1,0,0]
	v_pk_mul_f32 v[38:39], v[124:125], v[42:43]
	v_pk_mul_f32 v[28:29], v[28:29], v[14:15]
	v_pk_mul_f32 v[36:37], v[118:119], v[14:15]
	v_pk_fma_f32 v[14:15], v[126:127], v[14:15], v[38:39]
	v_pk_mul_f32 v[34:35], v[116:117], v[42:43]
	v_add_f32_e32 v14, v14, v15
	v_pk_fma_f32 v[26:27], v[26:27], v[42:43], v[28:29]
	s_waitcnt lgkmcnt(7)
	v_pk_fma_f32 v[42:43], v[16:17], v[30:31], v[34:35] op_sel_hi:[0,1,1]
	v_add_f32_dpp v66, v14, v14 quad_perm:[1,0,3,2] row_mask:0xf bank_mask:0xf bound_ctrl:1
	v_pk_fma_f32 v[44:45], v[16:17], v[32:33], v[36:37] op_sel_hi:[0,1,1]
	v_add_f32_e32 v93, v26, v27
	v_add_f32_dpp v66, v66, v66 quad_perm:[2,3,0,1] row_mask:0xf bank_mask:0xf bound_ctrl:1
	ds_read_b128 v[14:17], v90 offset:1024
	ds_read_b128 v[26:29], v89 offset:5120
	ds_read_b128 v[30:33], v90 offset:5120
	ds_read_b128 v[34:37], v90 offset:9216
	ds_read_b128 v[38:41], v89 offset:17408
	v_add_f32_dpp v66, v66, v66 row_half_mirror row_mask:0xf bank_mask:0xf bound_ctrl:1
	s_nop 1
	v_add_f32_dpp v66, v66, v66 row_ror:8 row_mask:0xf bank_mask:0xf bound_ctrl:1
	s_waitcnt lgkmcnt(11)
	v_pk_fma_f32 v[22:23], v[22:23], v[66:67], v[42:43] op_sel_hi:[1,0,1] neg_lo:[1,0,0] neg_hi:[1,0,0]
	v_pk_fma_f32 v[24:25], v[24:25], v[66:67], v[44:45] op_sel_hi:[1,0,1] neg_lo:[1,0,0] neg_hi:[1,0,0]
	s_waitcnt lgkmcnt(7)
	v_pk_mul_f32 v[42:43], v[54:55], v[22:23]
	v_pk_mul_f32 v[20:21], v[20:21], v[24:25]
	v_pk_mul_f32 v[44:45], v[46:47], v[22:23]
	v_pk_mul_f32 v[46:47], v[48:49], v[24:25]
	v_pk_fma_f32 v[18:19], v[18:19], v[22:23], v[20:21]
	v_pk_fma_f32 v[20:21], v[56:57], v[24:25], v[42:43]
	v_pk_fma_f32 v[54:55], v[0:1], v[50:51], v[44:45] op_sel_hi:[0,1,1]
	v_pk_fma_f32 v[56:57], v[0:1], v[52:53], v[46:47] op_sel_hi:[0,1,1]
	v_add_f32_e32 v94, v18, v19
	v_add_f32_e32 v18, v20, v21
	s_nop 0
	v_add_f32_dpp v0, v18, v18 quad_perm:[1,0,3,2] row_mask:0xf bank_mask:0xf bound_ctrl:1
	ds_read_b128 v[18:21], v90 offset:1280
	ds_read_b128 v[22:25], v89 offset:5376
	v_add_f32_dpp v0, v0, v0 quad_perm:[2,3,0,1] row_mask:0xf bank_mask:0xf bound_ctrl:1
	ds_read_b128 v[42:45], v90 offset:5376
	ds_read_b128 v[46:49], v90 offset:9472
	v_add_f32_dpp v0, v0, v0 row_half_mirror row_mask:0xf bank_mask:0xf bound_ctrl:1
	ds_read_b128 v[50:53], v89 offset:17664
	s_nop 0
	v_add_f32_dpp v0, v0, v0 row_ror:8 row_mask:0xf bank_mask:0xf bound_ctrl:1
	s_waitcnt lgkmcnt(11)
	v_pk_fma_f32 v[54:55], v[58:59], v[0:1], v[54:55] op_sel_hi:[1,0,1] neg_lo:[1,0,0] neg_hi:[1,0,0]
	v_pk_fma_f32 v[56:57], v[60:61], v[0:1], v[56:57] op_sel_hi:[1,0,1] neg_lo:[1,0,0] neg_hi:[1,0,0]
	s_waitcnt lgkmcnt(7)
	v_pk_mul_f32 v[30:31], v[30:31], v[54:55]
	v_pk_mul_f32 v[58:59], v[64:65], v[56:57]
	v_pk_mul_f32 v[14:15], v[14:15], v[54:55]
	v_pk_fma_f32 v[54:55], v[62:63], v[54:55], v[58:59]
	v_pk_fma_f32 v[30:31], v[32:33], v[56:57], v[30:31]
	v_pk_fma_f32 v[62:63], v[10:11], v[26:27], v[14:15] op_sel_hi:[0,1,1]
	v_add_f32_e32 v95, v54, v55
	v_add_f32_e32 v14, v30, v31
	ds_write_b128 v91, v[92:95] offset:43008
	v_pk_mul_f32 v[16:17], v[16:17], v[56:57]
	v_add_f32_dpp v0, v14, v14 quad_perm:[1,0,3,2] row_mask:0xf bank_mask:0xf bound_ctrl:1
	v_pk_fma_f32 v[64:65], v[10:11], v[28:29], v[16:17] op_sel_hi:[0,1,1]
	ds_read_b128 v[14:17], v90 offset:1536
	v_add_f32_dpp v0, v0, v0 quad_perm:[2,3,0,1] row_mask:0xf bank_mask:0xf bound_ctrl:1
	ds_read_b128 v[26:29], v89 offset:5632
	ds_read_b128 v[30:33], v90 offset:5632
	v_add_f32_dpp v0, v0, v0 row_half_mirror row_mask:0xf bank_mask:0xf bound_ctrl:1
	ds_read_b128 v[54:57], v90 offset:9728
	ds_read_b128 v[58:61], v89 offset:17920
	v_add_f32_dpp v0, v0, v0 row_ror:8 row_mask:0xf bank_mask:0xf bound_ctrl:1
	s_waitcnt lgkmcnt(12)
	v_pk_fma_f32 v[34:35], v[34:35], v[0:1], v[62:63] op_sel_hi:[1,0,1] neg_lo:[1,0,0] neg_hi:[1,0,0]
	v_pk_fma_f32 v[36:37], v[36:37], v[0:1], v[64:65] op_sel_hi:[1,0,1] neg_lo:[1,0,0] neg_hi:[1,0,0]
	s_waitcnt lgkmcnt(8)
	v_pk_mul_f32 v[42:43], v[42:43], v[34:35]
	v_pk_mul_f32 v[40:41], v[40:41], v[36:37]
	v_pk_mul_f32 v[18:19], v[18:19], v[34:35]
	v_pk_mul_f32 v[20:21], v[20:21], v[36:37]
	v_pk_fma_f32 v[34:35], v[38:39], v[34:35], v[40:41]
	v_pk_fma_f32 v[36:37], v[44:45], v[36:37], v[42:43]
	v_pk_fma_f32 v[62:63], v[10:11], v[22:23], v[18:19] op_sel:[1,0,0]
	v_add_f32_e32 v96, v34, v35
	v_add_f32_e32 v18, v36, v37
	v_pk_fma_f32 v[10:11], v[10:11], v[24:25], v[20:21] op_sel:[1,0,0]
	v_add_f32_dpp v0, v18, v18 quad_perm:[1,0,3,2] row_mask:0xf bank_mask:0xf bound_ctrl:1
	ds_read_b128 v[18:21], v90 offset:1792
	ds_read_b128 v[22:25], v89 offset:5888
	v_add_f32_dpp v0, v0, v0 quad_perm:[2,3,0,1] row_mask:0xf bank_mask:0xf bound_ctrl:1
	ds_read_b128 v[34:37], v90 offset:5888
	ds_read_b128 v[38:41], v90 offset:9984
	v_add_f32_dpp v0, v0, v0 row_half_mirror row_mask:0xf bank_mask:0xf bound_ctrl:1
	ds_read_b128 v[42:45], v89 offset:18176
	s_nop 0
	v_add_f32_dpp v0, v0, v0 row_ror:8 row_mask:0xf bank_mask:0xf bound_ctrl:1
	s_waitcnt lgkmcnt(12)
	v_pk_fma_f32 v[46:47], v[46:47], v[0:1], v[62:63] op_sel_hi:[1,0,1] neg_lo:[1,0,0] neg_hi:[1,0,0]
	v_pk_fma_f32 v[10:11], v[48:49], v[0:1], v[10:11] op_sel_hi:[1,0,1] neg_lo:[1,0,0] neg_hi:[1,0,0]
	s_waitcnt lgkmcnt(7)
	v_pk_mul_f32 v[30:31], v[30:31], v[46:47]
	v_pk_mul_f32 v[48:49], v[52:53], v[10:11]
	v_pk_mul_f32 v[14:15], v[14:15], v[46:47]
	v_pk_mul_f32 v[16:17], v[16:17], v[10:11]
	v_pk_fma_f32 v[46:47], v[50:51], v[46:47], v[48:49]
	v_pk_fma_f32 v[10:11], v[32:33], v[10:11], v[30:31]
	v_add_f32_e32 v97, v46, v47
	v_add_f32_e32 v10, v10, v11
	v_pk_fma_f32 v[50:51], v[12:13], v[26:27], v[14:15] op_sel_hi:[0,1,1]
	v_add_f32_dpp v0, v10, v10 quad_perm:[1,0,3,2] row_mask:0xf bank_mask:0xf bound_ctrl:1
	v_pk_fma_f32 v[52:53], v[12:13], v[28:29], v[16:17] op_sel_hi:[0,1,1]
	ds_read_b128 v[10:13], v90 offset:2048
	v_add_f32_dpp v0, v0, v0 quad_perm:[2,3,0,1] row_mask:0xf bank_mask:0xf bound_ctrl:1
	ds_read_b128 v[14:17], v89 offset:6144
	ds_read_b128 v[26:29], v90 offset:6144
	v_add_f32_dpp v0, v0, v0 row_half_mirror row_mask:0xf bank_mask:0xf bound_ctrl:1
	ds_read_b128 v[30:33], v90 offset:10240
	ds_read_b128 v[46:49], v89 offset:18432
	v_add_f32_dpp v0, v0, v0 row_ror:8 row_mask:0xf bank_mask:0xf bound_ctrl:1
	s_waitcnt lgkmcnt(11)
	v_pk_fma_f32 v[50:51], v[54:55], v[0:1], v[50:51] op_sel_hi:[1,0,1] neg_lo:[1,0,0] neg_hi:[1,0,0]
	v_pk_fma_f32 v[52:53], v[56:57], v[0:1], v[52:53] op_sel_hi:[1,0,1] neg_lo:[1,0,0] neg_hi:[1,0,0]
	s_waitcnt lgkmcnt(7)
	v_pk_mul_f32 v[34:35], v[34:35], v[50:51]
	v_pk_mul_f32 v[54:55], v[60:61], v[52:53]
	v_pk_mul_f32 v[18:19], v[18:19], v[50:51]
	v_pk_fma_f32 v[50:51], v[58:59], v[50:51], v[54:55]
	v_pk_fma_f32 v[34:35], v[36:37], v[52:53], v[34:35]
	v_pk_fma_f32 v[58:59], v[82:83], v[22:23], v[18:19] op_sel_hi:[0,1,1]
	v_add_f32_e32 v98, v50, v51
	v_add_f32_e32 v18, v34, v35
	v_pk_mul_f32 v[20:21], v[20:21], v[52:53]
	v_add_f32_dpp v0, v18, v18 quad_perm:[1,0,3,2] row_mask:0xf bank_mask:0xf bound_ctrl:1
	v_pk_fma_f32 v[60:61], v[82:83], v[24:25], v[20:21] op_sel_hi:[0,1,1]
	ds_read_b128 v[18:21], v90 offset:2304
	v_add_f32_dpp v0, v0, v0 quad_perm:[2,3,0,1] row_mask:0xf bank_mask:0xf bound_ctrl:1
	ds_read_b128 v[22:25], v89 offset:6400
	ds_read_b128 v[34:37], v90 offset:6400
	v_add_f32_dpp v0, v0, v0 row_half_mirror row_mask:0xf bank_mask:0xf bound_ctrl:1
	ds_read_b128 v[50:53], v90 offset:10496
	ds_read_b128 v[54:57], v89 offset:18688
	v_add_f32_dpp v0, v0, v0 row_ror:8 row_mask:0xf bank_mask:0xf bound_ctrl:1
	s_waitcnt lgkmcnt(11)
	v_pk_fma_f32 v[38:39], v[38:39], v[0:1], v[58:59] op_sel_hi:[1,0,1] neg_lo:[1,0,0] neg_hi:[1,0,0]
	v_pk_fma_f32 v[40:41], v[40:41], v[0:1], v[60:61] op_sel_hi:[1,0,1] neg_lo:[1,0,0] neg_hi:[1,0,0]
	s_waitcnt lgkmcnt(7)
	v_pk_mul_f32 v[26:27], v[26:27], v[38:39]
	v_pk_mul_f32 v[44:45], v[44:45], v[40:41]
	v_pk_mul_f32 v[10:11], v[10:11], v[38:39]
	v_pk_fma_f32 v[38:39], v[42:43], v[38:39], v[44:45]
	v_pk_fma_f32 v[26:27], v[28:29], v[40:41], v[26:27]
	v_pk_fma_f32 v[58:59], v[6:7], v[14:15], v[10:11] op_sel_hi:[0,1,1]
	v_add_f32_e32 v99, v38, v39
	v_add_f32_e32 v10, v26, v27
	ds_write_b128 v91, v[96:99] offset:47104
	v_pk_mul_f32 v[12:13], v[12:13], v[40:41]
	v_add_f32_dpp v0, v10, v10 quad_perm:[1,0,3,2] row_mask:0xf bank_mask:0xf bound_ctrl:1
	v_pk_fma_f32 v[60:61], v[6:7], v[16:17], v[12:13] op_sel_hi:[0,1,1]
	ds_read_b128 v[10:13], v90 offset:2560
	v_add_f32_dpp v0, v0, v0 quad_perm:[2,3,0,1] row_mask:0xf bank_mask:0xf bound_ctrl:1
	ds_read_b128 v[14:17], v89 offset:6656
	ds_read_b128 v[26:29], v90 offset:6656
	v_add_f32_dpp v0, v0, v0 row_half_mirror row_mask:0xf bank_mask:0xf bound_ctrl:1
	ds_read_b128 v[38:41], v90 offset:10752
	ds_read_b128 v[42:45], v89 offset:18944
	v_add_f32_dpp v0, v0, v0 row_ror:8 row_mask:0xf bank_mask:0xf bound_ctrl:1
	s_waitcnt lgkmcnt(12)
	v_pk_fma_f32 v[30:31], v[30:31], v[0:1], v[58:59] op_sel_hi:[1,0,1] neg_lo:[1,0,0] neg_hi:[1,0,0]
	v_pk_fma_f32 v[32:33], v[32:33], v[0:1], v[60:61] op_sel_hi:[1,0,1] neg_lo:[1,0,0] neg_hi:[1,0,0]
	s_waitcnt lgkmcnt(8)
	v_pk_mul_f32 v[34:35], v[34:35], v[30:31]
	v_pk_mul_f32 v[48:49], v[48:49], v[32:33]
	v_pk_mul_f32 v[18:19], v[18:19], v[30:31]
	v_pk_mul_f32 v[20:21], v[20:21], v[32:33]
	v_pk_fma_f32 v[30:31], v[46:47], v[30:31], v[48:49]
	v_pk_fma_f32 v[32:33], v[36:37], v[32:33], v[34:35]
	v_pk_fma_f32 v[58:59], v[6:7], v[22:23], v[18:19] op_sel:[1,0,0]
	v_add_f32_e32 v92, v30, v31
	v_add_f32_e32 v18, v32, v33
	v_pk_fma_f32 v[6:7], v[6:7], v[24:25], v[20:21] op_sel:[1,0,0]
	v_add_f32_dpp v0, v18, v18 quad_perm:[1,0,3,2] row_mask:0xf bank_mask:0xf bound_ctrl:1
	ds_read_b128 v[18:21], v90 offset:2816
	ds_read_b128 v[22:25], v89 offset:6912
	v_add_f32_dpp v0, v0, v0 quad_perm:[2,3,0,1] row_mask:0xf bank_mask:0xf bound_ctrl:1
	ds_read_b128 v[30:33], v90 offset:6912
	ds_read_b128 v[34:37], v90 offset:11008
	v_add_f32_dpp v0, v0, v0 row_half_mirror row_mask:0xf bank_mask:0xf bound_ctrl:1
	ds_read_b128 v[46:49], v89 offset:19200
	s_nop 0
	v_add_f32_dpp v0, v0, v0 row_ror:8 row_mask:0xf bank_mask:0xf bound_ctrl:1
	s_waitcnt lgkmcnt(12)
	v_pk_fma_f32 v[50:51], v[50:51], v[0:1], v[58:59] op_sel_hi:[1,0,1] neg_lo:[1,0,0] neg_hi:[1,0,0]
	v_pk_fma_f32 v[6:7], v[52:53], v[0:1], v[6:7] op_sel_hi:[1,0,1] neg_lo:[1,0,0] neg_hi:[1,0,0]
	s_waitcnt lgkmcnt(7)
	v_pk_mul_f32 v[26:27], v[26:27], v[50:51]
	v_pk_mul_f32 v[52:53], v[56:57], v[6:7]
	v_pk_mul_f32 v[10:11], v[10:11], v[50:51]
	v_pk_mul_f32 v[12:13], v[12:13], v[6:7]
	v_pk_fma_f32 v[50:51], v[54:55], v[50:51], v[52:53]
	v_pk_fma_f32 v[6:7], v[28:29], v[6:7], v[26:27]
	v_add_f32_e32 v93, v50, v51
	v_add_f32_e32 v6, v6, v7
	v_pk_fma_f32 v[54:55], v[8:9], v[14:15], v[10:11] op_sel_hi:[0,1,1]
	v_add_f32_dpp v0, v6, v6 quad_perm:[1,0,3,2] row_mask:0xf bank_mask:0xf bound_ctrl:1
	v_pk_fma_f32 v[56:57], v[8:9], v[16:17], v[12:13] op_sel_hi:[0,1,1]
	ds_read_b128 v[6:9], v90 offset:3072
	v_add_f32_dpp v0, v0, v0 quad_perm:[2,3,0,1] row_mask:0xf bank_mask:0xf bound_ctrl:1
	ds_read_b128 v[10:13], v89 offset:7168
	ds_read_b128 v[14:17], v90 offset:7168
	v_add_f32_dpp v0, v0, v0 row_half_mirror row_mask:0xf bank_mask:0xf bound_ctrl:1
	ds_read_b128 v[26:29], v90 offset:11264
	ds_read_b128 v[50:53], v89 offset:19456
	v_add_f32_dpp v0, v0, v0 row_ror:8 row_mask:0xf bank_mask:0xf bound_ctrl:1
	s_waitcnt lgkmcnt(11)
	v_pk_fma_f32 v[38:39], v[38:39], v[0:1], v[54:55] op_sel_hi:[1,0,1] neg_lo:[1,0,0] neg_hi:[1,0,0]
	v_pk_fma_f32 v[40:41], v[40:41], v[0:1], v[56:57] op_sel_hi:[1,0,1] neg_lo:[1,0,0] neg_hi:[1,0,0]
	s_waitcnt lgkmcnt(7)
	v_pk_mul_f32 v[30:31], v[30:31], v[38:39]
	v_pk_mul_f32 v[44:45], v[44:45], v[40:41]
	v_pk_mul_f32 v[18:19], v[18:19], v[38:39]
	v_pk_fma_f32 v[38:39], v[42:43], v[38:39], v[44:45]
	v_pk_fma_f32 v[30:31], v[32:33], v[40:41], v[30:31]
	v_pk_fma_f32 v[54:55], v[84:85], v[22:23], v[18:19] op_sel_hi:[0,1,1]
	v_add_f32_e32 v94, v38, v39
	v_add_f32_e32 v18, v30, v31
	v_pk_mul_f32 v[20:21], v[20:21], v[40:41]
	v_add_f32_dpp v0, v18, v18 quad_perm:[1,0,3,2] row_mask:0xf bank_mask:0xf bound_ctrl:1
	v_pk_fma_f32 v[56:57], v[84:85], v[24:25], v[20:21] op_sel_hi:[0,1,1]
	ds_read_b128 v[18:21], v90 offset:3328
	v_add_f32_dpp v0, v0, v0 quad_perm:[2,3,0,1] row_mask:0xf bank_mask:0xf bound_ctrl:1
	ds_read_b128 v[22:25], v89 offset:7424
	ds_read_b128 v[30:33], v90 offset:7424
	v_add_f32_dpp v0, v0, v0 row_half_mirror row_mask:0xf bank_mask:0xf bound_ctrl:1
	ds_read_b128 v[38:41], v90 offset:11520
	ds_read_b128 v[42:45], v89 offset:19712
	v_add_f32_dpp v0, v0, v0 row_ror:8 row_mask:0xf bank_mask:0xf bound_ctrl:1
	s_waitcnt lgkmcnt(11)
	v_pk_fma_f32 v[34:35], v[34:35], v[0:1], v[54:55] op_sel_hi:[1,0,1] neg_lo:[1,0,0] neg_hi:[1,0,0]
	v_pk_fma_f32 v[36:37], v[36:37], v[0:1], v[56:57] op_sel_hi:[1,0,1] neg_lo:[1,0,0] neg_hi:[1,0,0]
	s_waitcnt lgkmcnt(7)
	v_pk_mul_f32 v[14:15], v[14:15], v[34:35]
	v_pk_mul_f32 v[48:49], v[48:49], v[36:37]
	v_pk_mul_f32 v[6:7], v[6:7], v[34:35]
	v_pk_fma_f32 v[34:35], v[46:47], v[34:35], v[48:49]
	v_pk_fma_f32 v[14:15], v[16:17], v[36:37], v[14:15]
	v_pk_fma_f32 v[54:55], v[2:3], v[10:11], v[6:7] op_sel_hi:[0,1,1]
	v_add_f32_e32 v95, v34, v35
	v_add_f32_e32 v6, v14, v15
	ds_write_b128 v91, v[92:95] offset:51200
	v_pk_mul_f32 v[8:9], v[8:9], v[36:37]
	v_add_f32_dpp v0, v6, v6 quad_perm:[1,0,3,2] row_mask:0xf bank_mask:0xf bound_ctrl:1
	v_pk_fma_f32 v[56:57], v[2:3], v[12:13], v[8:9] op_sel_hi:[0,1,1]
	ds_read_b128 v[6:9], v90 offset:3584
	v_add_f32_dpp v0, v0, v0 quad_perm:[2,3,0,1] row_mask:0xf bank_mask:0xf bound_ctrl:1
	ds_read_b128 v[10:13], v89 offset:7680
	ds_read_b128 v[14:17], v90 offset:7680
	v_add_f32_dpp v0, v0, v0 row_half_mirror row_mask:0xf bank_mask:0xf bound_ctrl:1
	ds_read_b128 v[34:37], v90 offset:11776
	ds_read_b128 v[46:49], v89 offset:19968
	v_add_f32_dpp v0, v0, v0 row_ror:8 row_mask:0xf bank_mask:0xf bound_ctrl:1
	s_waitcnt lgkmcnt(12)
	v_pk_fma_f32 v[26:27], v[26:27], v[0:1], v[54:55] op_sel_hi:[1,0,1] neg_lo:[1,0,0] neg_hi:[1,0,0]
	v_pk_fma_f32 v[28:29], v[28:29], v[0:1], v[56:57] op_sel_hi:[1,0,1] neg_lo:[1,0,0] neg_hi:[1,0,0]
	s_waitcnt lgkmcnt(8)
	v_pk_mul_f32 v[30:31], v[30:31], v[26:27]
	v_pk_mul_f32 v[52:53], v[52:53], v[28:29]
	v_pk_mul_f32 v[18:19], v[18:19], v[26:27]
	v_pk_mul_f32 v[20:21], v[20:21], v[28:29]
	v_pk_fma_f32 v[26:27], v[50:51], v[26:27], v[52:53]
	v_pk_fma_f32 v[28:29], v[32:33], v[28:29], v[30:31]
	v_pk_fma_f32 v[54:55], v[2:3], v[22:23], v[18:19] op_sel:[1,0,0]
	v_add_f32_e32 v96, v26, v27
	v_add_f32_e32 v18, v28, v29
	v_pk_fma_f32 v[2:3], v[2:3], v[24:25], v[20:21] op_sel:[1,0,0]
	v_add_f32_dpp v0, v18, v18 quad_perm:[1,0,3,2] row_mask:0xf bank_mask:0xf bound_ctrl:1
	ds_read_b128 v[18:21], v90 offset:3840
	ds_read_b128 v[22:25], v89 offset:7936
	v_add_f32_dpp v0, v0, v0 quad_perm:[2,3,0,1] row_mask:0xf bank_mask:0xf bound_ctrl:1
	ds_read_b128 v[26:29], v90 offset:7936
	ds_read_b128 v[30:33], v90 offset:12032
	v_add_f32_dpp v0, v0, v0 row_half_mirror row_mask:0xf bank_mask:0xf bound_ctrl:1
	ds_read_b128 v[50:53], v89 offset:20224
	s_nop 0
	v_add_f32_dpp v0, v0, v0 row_ror:8 row_mask:0xf bank_mask:0xf bound_ctrl:1
	s_waitcnt lgkmcnt(12)
	v_pk_fma_f32 v[38:39], v[38:39], v[0:1], v[54:55] op_sel_hi:[1,0,1] neg_lo:[1,0,0] neg_hi:[1,0,0]
	v_pk_fma_f32 v[2:3], v[40:41], v[0:1], v[2:3] op_sel_hi:[1,0,1] neg_lo:[1,0,0] neg_hi:[1,0,0]
	s_waitcnt lgkmcnt(7)
	v_pk_mul_f32 v[14:15], v[14:15], v[38:39]
	v_pk_mul_f32 v[40:41], v[44:45], v[2:3]
	v_pk_mul_f32 v[8:9], v[8:9], v[2:3]
	v_pk_fma_f32 v[2:3], v[16:17], v[2:3], v[14:15]
	v_pk_mul_f32 v[6:7], v[6:7], v[38:39]
	v_add_f32_e32 v0, v2, v3
	v_pk_fma_f32 v[6:7], v[4:5], v[10:11], v[6:7] op_sel_hi:[0,1,1]
	v_pk_fma_f32 v[4:5], v[4:5], v[12:13], v[8:9] op_sel_hi:[0,1,1]
	v_add_f32_dpp v0, v0, v0 quad_perm:[1,0,3,2] row_mask:0xf bank_mask:0xf bound_ctrl:1
	v_pk_fma_f32 v[38:39], v[42:43], v[38:39], v[40:41]
	ds_read_b128 v[108:111], v88 offset:4096
	v_add_f32_dpp v0, v0, v0 quad_perm:[2,3,0,1] row_mask:0xf bank_mask:0xf bound_ctrl:1
	v_add_f32_e32 v97, v38, v39
	ds_read_b128 v[100:103], v88
	v_add_f32_dpp v0, v0, v0 row_half_mirror row_mask:0xf bank_mask:0xf bound_ctrl:1
	ds_read_b128 v[120:123], v88 offset:8192
	ds_read_b128 v[112:115], v88 offset:4352
	v_add_f32_dpp v0, v0, v0 row_ror:8 row_mask:0xf bank_mask:0xf bound_ctrl:1
	s_waitcnt lgkmcnt(10)
	v_pk_fma_f32 v[2:3], v[34:35], v[0:1], v[6:7] op_sel_hi:[1,0,1] neg_lo:[1,0,0] neg_hi:[1,0,0]
	v_pk_fma_f32 v[4:5], v[36:37], v[0:1], v[4:5] op_sel_hi:[1,0,1] neg_lo:[1,0,0] neg_hi:[1,0,0]
	s_waitcnt lgkmcnt(6)
	v_pk_mul_f32 v[8:9], v[26:27], v[2:3]
	v_pk_mul_f32 v[6:7], v[48:49], v[4:5]
	v_pk_mul_f32 v[10:11], v[18:19], v[2:3]
	v_pk_mul_f32 v[12:13], v[20:21], v[4:5]
	v_pk_fma_f32 v[2:3], v[46:47], v[2:3], v[6:7]
	v_pk_fma_f32 v[4:5], v[28:29], v[4:5], v[8:9]
	v_add_f32_e32 v98, v2, v3
	v_add_f32_e32 v2, v4, v5
	v_pk_fma_f32 v[8:9], v[86:87], v[24:25], v[12:13] op_sel_hi:[0,1,1]
	v_add_f32_dpp v0, v2, v2 quad_perm:[1,0,3,2] row_mask:0xf bank_mask:0xf bound_ctrl:1
	v_pk_fma_f32 v[6:7], v[86:87], v[22:23], v[10:11] op_sel_hi:[0,1,1]
	ds_read_b128 v[104:107], v88 offset:256
	v_add_f32_dpp v0, v0, v0 quad_perm:[2,3,0,1] row_mask:0xf bank_mask:0xf bound_ctrl:1
	ds_read_b128 v[128:131], v88 offset:8448
	ds_read_b128 v[124:127], v88 offset:4608
	v_add_f32_dpp v0, v0, v0 row_half_mirror row_mask:0xf bank_mask:0xf bound_ctrl:1
	ds_read_b128 v[116:119], v88 offset:512
	s_nop 0
	v_add_f32_dpp v0, v0, v0 row_ror:8 row_mask:0xf bank_mask:0xf bound_ctrl:1
	s_waitcnt lgkmcnt(9)
	v_pk_fma_f32 v[76:77], v[32:33], v[0:1], v[8:9] op_sel_hi:[1,0,1] neg_lo:[1,0,0] neg_hi:[1,0,0]
	v_pk_fma_f32 v[74:75], v[30:31], v[0:1], v[6:7] op_sel_hi:[1,0,1] neg_lo:[1,0,0] neg_hi:[1,0,0]
	s_waitcnt lgkmcnt(8)
	v_pk_mul_f32 v[2:3], v[52:53], v[76:77]
	s_nop 0
	v_pk_fma_f32 v[2:3], v[50:51], v[74:75], v[2:3]
	s_nop 0
	v_add_f32_e32 v99, v2, v3
	ds_write_b128 v91, v[96:99] offset:55296
	s_waitcnt lgkmcnt(0)
	s_barrier
	s_cbranch_scc0 .LBB0_1050
	s_setprio 0

.LBB0_1102:
	v_ashrrev_i32_e32 v45, 31, v44
	v_lshlrev_b64 v[26:27], 1, v[44:45]
	v_or_b32_e32 v26, s37, v26
	v_readlane_b32 s2, v252, 0
	v_readlane_b32 s4, v252, 6
	v_or_b32_e32 v43, s61, v90
	v_sub_u32_e32 v46, s27, v90
	v_lshlrev_b64 v[30:31], 10, v[26:27]
	v_readlane_b32 s3, v252, 1
	v_lshlrev_b64 v[26:27], 9, v[26:27]
	v_readlane_b32 s5, v252, 7
	v_cndmask_b32_e64 v46, v46, v43, s[16:17]
	v_lshl_add_u64 v[28:29], s[2:3], 0, v[30:31]
	v_lshl_add_u64 v[26:27], s[4:5], 0, v[26:27]
	v_mov_b32_e32 v41, v1
	v_ashrrev_i32_e32 v47, 31, v46
	v_readlane_b32 s8, v252, 10
	v_lshl_add_u64 v[28:29], v[28:29], 0, v[0:1]
	v_lshl_add_u64 v[32:33], v[26:27], 0, v[40:41]
	v_readlane_b32 s10, v252, 20
	v_readlane_b32 s12, v252, 22
	v_readlane_b32 s6, v252, 8
	v_lshlrev_b64 v[46:47], 9, v[46:47]
	v_readlane_b32 s9, v252, 11
	v_add_u32_e32 v124, 0x1b800, v123
	s_nop 0
	v_readfirstlane_b32 s98, v124
	s_mov_b32 m0, s98
	s_nop 0
	global_load_lds_dwordx4 v[28:29], off
	s_nop 0
	global_load_dwordx2 v[82:83], v[32:33], off
	v_lshlrev_b64 v[32:33], 10, v[44:45]
	v_readlane_b32 s11, v252, 21
	v_readlane_b32 s13, v252, 23
	v_lshlrev_b64 v[44:45], 9, v[44:45]
	v_readlane_b32 s7, v252, 9
	v_lshl_add_u64 v[46:47], s[8:9], 0, v[46:47]
	s_mov_b32 s27, s21
	v_lshl_add_u64 v[32:33], s[10:11], 0, v[32:33]
	v_lshl_add_u64 v[30:31], s[12:13], 0, v[30:31]
	v_lshl_add_u64 v[44:45], s[6:7], 0, v[44:45]
	v_lshl_add_u64 v[46:47], v[46:47], 0, s[26:27]
	s_mov_b32 s49, s21
	v_lshl_add_u64 v[32:33], v[32:33], 0, v[0:1]
	v_lshl_add_u64 v[34:35], v[30:31], 0, v[0:1]
	v_lshl_add_u64 v[44:45], v[44:45], 0, v[40:41]
	v_lshl_add_u64 v[46:47], v[46:47], 0, s[48:49]
	v_mov_b32_e32 v43, v1
	v_add_u32_e32 v124, 0x1c800, v123
	s_nop 0
	v_readfirstlane_b32 s98, v124
	s_mov_b32 m0, s98
	s_nop 0
	global_load_lds_dwordx4 v[32:33], off
	s_nop 0
	v_add_u32_e32 v124, 0x1d800, v123
	s_nop 0
	v_readfirstlane_b32 s98, v124
	s_mov_b32 m0, s98
	s_nop 0
	global_load_lds_dwordx4 v[34:35], off
	v_lshl_add_u64 v[46:47], v[46:47], 0, v[42:43]
	global_load_dwordx2 v[84:85], v[44:45], off
	global_load_dwordx2 v[86:87], v[46:47], off
	s_lshl_b32 s20, s37, 10
	v_lshl_add_u64 v[60:61], s[2:3], 0, v[0:1]
	s_add_u32 s2, s8, s26
	s_addc_u32 s3, s9, 0
	s_add_u32 s26, s2, s48
	s_addc_u32 s27, s3, 0
	v_readlane_b32 s2, v252, 14
	v_readlane_b32 s3, v252, 15
	s_add_u32 s2, s2, s20
	s_addc_u32 s3, s3, 0
	s_lshl_b32 s48, s60, 2
	s_add_u32 s2, s2, s48
	s_addc_u32 s3, s3, 0
	s_lshl_b32 s50, s33, 2
	s_waitcnt vmcnt(12)
	s_waitcnt lgkmcnt(0)
	s_barrier
	v_lshl_add_u64 v[70:71], s[26:27], 0, v[42:43]
	s_add_u32 s26, s2, s50
	v_lshl_add_u64 v[64:65], s[10:11], 0, v[0:1]
	v_lshl_add_u64 v[66:67], s[12:13], 0, v[0:1]
	v_lshlrev_b32_e32 v0, 6, v39
	v_lshrrev_b32_e32 v94, 2, v39
	s_addc_u32 s27, s3, 0
	v_mov_b32_e32 v39, v1
	v_lshl_add_u64 v[62:63], s[4:5], 0, v[40:41]
	v_lshl_add_u64 v[68:69], s[6:7], 0, v[40:41]
	v_and_b32_e32 v93, 0xc0, v0
	v_add_u32_e32 v0, 0, v0
	v_lshl_add_u64 v[72:73], s[26:27], 0, v[38:39]
	s_sub_i32 s98, 1, s37
	s_sub_i32 s98, s98, s37
	s_ashr_i32 s99, s98, 31
	v_mov_b32_e32 v112, s98
	v_mov_b32_e32 v113, s99
	s_cmp_eq_u32 s37, 0
	s_cselect_b32 s98, 64, 0xbf
	s_add_i32 s98, s98, s25
	v_mov_b32_e32 v110, s98
	v_mad_i32_i24 v111, v55, v112, v110
	v_and_b32_e32 v108, 63, v232
	v_lshrrev_b32_e32 v108, 2, v108
	v_mad_i32_i24 v109, v108, v112, v110
	v_lshl_or_b32 v108, v111, 1, s37
	s_movk_i32 s98, 0x400
	s_movk_i32 s99, 0x200
	v_mad_u64_u32 v[96:97], vcc, v108, s98, v[60:61]
	v_mad_u64_u32 v[98:99], vcc, v108, s99, v[62:63]
	v_mad_u64_u32 v[100:101], vcc, v111, s98, v[64:65]
	v_mad_u64_u32 v[102:103], vcc, v108, s98, v[66:67]
	v_mad_u64_u32 v[104:105], vcc, v111, s99, v[68:69]
	v_mad_u64_u32 v[106:107], vcc, v109, s99, v[70:71]
	s_cmp_eq_u32 s37, 0
	s_cselect_b32 s98, 0, 0xff
	s_add_i32 s98, s98, s25
	v_mov_b32_e32 v110, s98
	v_mad_i32_i24 v111, v55, v112, v110
	s_movk_i32 s98, 0x800
	v_mad_u64_u32 v[108:109], vcc, v111, s98, v[72:73]
	v_and_b32_e32 v126, 0xff, v232
	v_lshrrev_b32_e32 v127, 6, v126
	v_and_b32_e32 v128, 3, v126
	v_lshl_add_u32 v127, v127, 2, v128
	v_lshrrev_b32_e32 v128, 4, v126
	v_sub_u32_e32 v127, v127, v128
	v_mul_i32_i24_e32 v127, v127, v112
	v_lshlrev_b32_e32 v127, 11, v127
	v_bfe_u32 v128, v126, 2, 4
	v_and_b32_e32 v129, 15, v126
	v_sub_u32_e32 v128, v128, v129
	v_lshl_add_u32 v128, v128, 2, v127
	v_ashrrev_i32_e32 v129, 31, v128
	v_lshl_add_u64 v[108:109], v[128:129], 0, v[108:109]
	s_sub_i32 s98, s24, s25
	s_movk_i32 s99, 0x1000
	s_cmp_eq_u32 s37, 0
	s_cselect_b32 s99, 0xffffff00, s99
	s_add_i32 s98, s98, s99
	s_lshl_b32 s98, s98, 9
	s_ashr_i32 s99, s98, 31
	v_mov_b32_e32 v120, s98
	v_mov_b32_e32 v121, s99
	s_lshl_b32 s98, s98, 1
	v_mov_b32_e32 v118, s98
	v_mov_b32_e32 v119, s99
	s_lshl_b32 s98, s98, 1
	v_mov_b32_e32 v110, s98
	v_mov_b32_e32 v111, s99
	v_lshlrev_b32_e32 v112, 15, v112
	v_ashrrev_i32_e32 v114, 1, v112
	v_mov_b32_e32 v115, v113
	v_ashrrev_i32_e32 v116, 2, v112
	v_mov_b32_e32 v117, v113
	s_mov_b32 s49, 0
	s_mov_b32 s51, 0
	s_branch .LBB0_1106

.Lscan_y_nofix:
	global_store_dword v[108:109], v40, off
	v_lshl_add_u64 v[108:109], v[112:113], 0, v[108:109]
	s_waitcnt vmcnt(17)
	s_waitcnt lgkmcnt(0)
	s_barrier

.LBB0_1162:
	s_waitcnt vmcnt(17)
	s_waitcnt lgkmcnt(0)
	s_barrier
	s_cmpk_lt_u32 s49, 6
	s_cbranch_scc1 .Lscan_ld_drain_b
	s_cmpk_lt_u32 s49, 0x109
	s_cbranch_scc1 .Lscan_ld_steady_b

.LBB0_1221:
	s_waitcnt lgkmcnt(2)
	v_pk_add_f32 v[48:49], v[48:49], v[52:53]
	v_pk_add_f32 v[46:47], v[46:47], v[50:51]
	s_waitcnt lgkmcnt(0)
	v_pk_add_f32 v[40:41], v[40:41], v[44:45]
	v_pk_add_f32 v[38:39], v[38:39], v[42:43]
	v_pk_add_f32 v[40:41], v[48:49], v[40:41]
	v_pk_add_f32 v[38:39], v[46:47], v[38:39]
	s_nop 1
	v_add_f32_dpp v38, v38, v38 quad_perm:[1,0,3,2] row_mask:0xf bank_mask:0xf bound_ctrl:1
	v_add_f32_dpp v39, v39, v39 quad_perm:[1,0,3,2] row_mask:0xf bank_mask:0xf bound_ctrl:1
	v_add_f32_dpp v40, v40, v40 quad_perm:[1,0,3,2] row_mask:0xf bank_mask:0xf bound_ctrl:1
	v_add_f32_dpp v41, v41, v41 quad_perm:[1,0,3,2] row_mask:0xf bank_mask:0xf bound_ctrl:1
	v_add_f32_dpp v38, v38, v38 quad_perm:[2,3,0,1] row_mask:0xf bank_mask:0xf bound_ctrl:1
	v_add_f32_dpp v39, v39, v39 quad_perm:[2,3,0,1] row_mask:0xf bank_mask:0xf bound_ctrl:1
	v_add_f32_dpp v40, v40, v40 quad_perm:[2,3,0,1] row_mask:0xf bank_mask:0xf bound_ctrl:1
	v_add_f32_dpp v41, v41, v41 quad_perm:[2,3,0,1] row_mask:0xf bank_mask:0xf bound_ctrl:1
	s_andn2_b64 vcc, exec, s[60:61]
	v_cmp_eq_u32_e64 s[2:3], 1, v125
	s_nop 1
	v_cndmask_b32_e64 v38, v38, v39, s[2:3]
	v_cmp_eq_u32_e64 s[2:3], 2, v125
	s_nop 1
	v_cndmask_b32_e64 v38, v38, v40, s[2:3]
	v_cmp_eq_u32_e64 s[2:3], 3, v125
	s_nop 1
	v_cndmask_b32_e64 v40, v38, v41, s[2:3]
	global_store_dword v[108:109], v40, off
	v_lshl_add_u64 v[108:109], v[112:113], 0, v[108:109]
	s_waitcnt vmcnt(17)
	s_waitcnt lgkmcnt(0)
	s_barrier
	s_cmpk_lt_u32 s49, 6
	s_cbranch_scc1 .Lscan_ld_drain_c
	s_cmpk_lt_u32 s49, 0x109
	s_cbranch_scc1 .Lscan_ld_steady_c
